# combo8 + GEMM K-loops: static issue priority, older wave half (waves 0-3) at 1 and younger at 0 for the whole K-loop, no per-segment s_setprio flips
# speedup vs baseline: 1.0122x; 1.0012x over previous
; template <class Epi>
; __device__ __forceinline__ void gemm_phase(LAS unsigned char* lds, const Gemm g, const StaticOrder& S, const Epi& E, const int tid) {
;     ...
;         const bool has_next = S.next(ui + 1, nxt);
;         const char* nA = has_next ? PG8_APTR(nxt) : cA; const char* nB = has_next ? PG8_BPTR(nxt) : cB;
;     ...
;         for (int a = 0; a < 2; ++a)
; #pragma unroll
;             for (int b = 0; b < 2; ++b)
; #pragma unroll
;                 for (int m = 0; m < 4; ++m)
; #pragma unroll
;                     for (int n = 0; n < 2; ++n) acc[a][b][m][n] = (f32x4){0.f, 0.f, 0.f, 0.f};
.LBB0_160:
	s_ashr_i32 s15, s14, 31
	s_lshl_b64 s[16:17], s[14:15], 20
	s_add_u32 s16, s58, s16
	s_addc_u32 s17, s59, s17
	s_and_b64 s[18:19], s[36:37], exec
	s_cselect_b32 s15, s17, s35
	s_cselect_b32 s53, s16, s34
	s_ashr_i32 s13, s12, 31
	s_lshl_b64 s[18:19], s[12:13], 20
	s_add_u32 s18, s40, s18
	s_addc_u32 s19, s41, s19
	s_and_b64 s[38:39], s[36:37], exec
	s_cselect_b32 s13, s19, s1
	s_cselect_b32 s56, s18, s0
	s_add_u32 s34, s34, 0x80080
	s_addc_u32 s35, s35, 0
	s_add_u32 s57, s0, 0x100
	v_mov_b32_e32 v0, 0
	s_addc_u32 s58, s1, 0
	s_mov_b32 s59, -2
	v_mov_b32_e32 v1, v0
	v_mov_b32_e32 v2, v0
	v_mov_b32_e32 v3, v0
	v_mov_b32_e32 v8, v0
	v_mov_b32_e32 v9, v0
	v_mov_b32_e32 v10, v0
	v_mov_b32_e32 v11, v0
	v_mov_b32_e32 v16, v0
	v_mov_b32_e32 v17, v0
	v_mov_b32_e32 v18, v0
	v_mov_b32_e32 v19, v0
	v_mov_b32_e32 v24, v0
	v_mov_b32_e32 v25, v0
	v_mov_b32_e32 v26, v0
	v_mov_b32_e32 v27, v0
	v_mov_b32_e32 v32, v0
	v_mov_b32_e32 v33, v0
	v_mov_b32_e32 v34, v0
	v_mov_b32_e32 v35, v0
	v_mov_b32_e32 v40, v0
	v_mov_b32_e32 v41, v0
	v_mov_b32_e32 v42, v0
	v_mov_b32_e32 v43, v0
	v_mov_b32_e32 v48, v0
	v_mov_b32_e32 v49, v0
	v_mov_b32_e32 v50, v0
	v_mov_b32_e32 v51, v0
	v_mov_b32_e32 v56, v0
	v_mov_b32_e32 v57, v0
	v_mov_b32_e32 v58, v0
	v_mov_b32_e32 v59, v0
	v_mov_b32_e32 v4, v0
	v_mov_b32_e32 v5, v0
	v_mov_b32_e32 v6, v0
	v_mov_b32_e32 v7, v0
	v_mov_b32_e32 v12, v0
	v_mov_b32_e32 v13, v0
	v_mov_b32_e32 v14, v0
	v_mov_b32_e32 v15, v0
	v_mov_b32_e32 v20, v0
	v_mov_b32_e32 v21, v0
	v_mov_b32_e32 v22, v0
	v_mov_b32_e32 v23, v0
	v_mov_b32_e32 v28, v0
	v_mov_b32_e32 v29, v0
	v_mov_b32_e32 v30, v0
	v_mov_b32_e32 v31, v0
	v_mov_b32_e32 v36, v0
	v_mov_b32_e32 v37, v0
	v_mov_b32_e32 v38, v0
	v_mov_b32_e32 v39, v0
	v_mov_b32_e32 v44, v0
	v_mov_b32_e32 v45, v0
	v_mov_b32_e32 v46, v0
	v_mov_b32_e32 v47, v0
	v_mov_b32_e32 v52, v0
	v_mov_b32_e32 v53, v0
	v_mov_b32_e32 v54, v0
	v_mov_b32_e32 v55, v0
	v_mov_b32_e32 v60, v0
	v_mov_b32_e32 v61, v0
	v_mov_b32_e32 v62, v0
	v_mov_b32_e32 v63, v0
	v_mov_b32_e32 v64, v0
	v_mov_b32_e32 v65, v0
	v_mov_b32_e32 v66, v0
	v_mov_b32_e32 v67, v0
	v_mov_b32_e32 v72, v0
	v_mov_b32_e32 v73, v0
	v_mov_b32_e32 v74, v0
	v_mov_b32_e32 v75, v0
	v_mov_b32_e32 v80, v0
	v_mov_b32_e32 v81, v0
	v_mov_b32_e32 v82, v0
	v_mov_b32_e32 v83, v0
	v_mov_b32_e32 v88, v0
	v_mov_b32_e32 v89, v0
	v_mov_b32_e32 v90, v0
	v_mov_b32_e32 v91, v0
	v_mov_b32_e32 v96, v0
	v_mov_b32_e32 v97, v0
	v_mov_b32_e32 v98, v0
	v_mov_b32_e32 v99, v0
	v_mov_b32_e32 v104, v0
	v_mov_b32_e32 v105, v0
	v_mov_b32_e32 v106, v0
	v_mov_b32_e32 v107, v0
	v_mov_b32_e32 v112, v0
	v_mov_b32_e32 v113, v0
	v_mov_b32_e32 v114, v0
	v_mov_b32_e32 v115, v0
	v_mov_b32_e32 v120, v0
	v_mov_b32_e32 v121, v0
	v_mov_b32_e32 v122, v0
	v_mov_b32_e32 v123, v0
	v_mov_b32_e32 v68, v0
	v_mov_b32_e32 v69, v0
	v_mov_b32_e32 v70, v0
	v_mov_b32_e32 v71, v0
	v_mov_b32_e32 v76, v0
	v_mov_b32_e32 v77, v0
	v_mov_b32_e32 v78, v0
	v_mov_b32_e32 v79, v0
	v_mov_b32_e32 v84, v0
	v_mov_b32_e32 v85, v0
	v_mov_b32_e32 v86, v0
	v_mov_b32_e32 v87, v0
	v_mov_b32_e32 v92, v0
	v_mov_b32_e32 v93, v0
	v_mov_b32_e32 v94, v0
	v_mov_b32_e32 v95, v0
	v_mov_b32_e32 v100, v0
	v_mov_b32_e32 v101, v0
	v_mov_b32_e32 v102, v0
	v_mov_b32_e32 v103, v0
	v_mov_b32_e32 v108, v0
	v_mov_b32_e32 v109, v0
	v_mov_b32_e32 v110, v0
	v_mov_b32_e32 v111, v0
	v_mov_b32_e32 v116, v0
	v_mov_b32_e32 v117, v0
	v_mov_b32_e32 v118, v0
	v_mov_b32_e32 v119, v0
	v_mov_b32_e32 v124, v0
	v_mov_b32_e32 v125, v0
	v_mov_b32_e32 v126, v0
	v_mov_b32_e32 v127, v0
	s_cmp_lg_u64 s[10:11], 0
	s_cbranch_scc0 .Lgprio_a
	s_setprio 1

; template <class Epi>
; __device__ __forceinline__ void gemm_phase(LAS unsigned char* lds, const Gemm g, const StaticOrder& S, const Epi& E, const int tid) {
;     ...
;         for (int a = 0; a < 2; ++a)
; #pragma unroll
;             for (int b = 0; b < 2; ++b)
; #pragma unroll
;                 for (int m = 0; m < 4; ++m)
; #pragma unroll
;                     for (int n = 0; n < 2; ++n) acc[a][b][m][n] = (f32x4){0.f, 0.f, 0.f, 0.f};
.LBB0_232:
	s_add_u32 s42, s0, 0x100
	v_mov_b32_e32 v0, 0
	s_addc_u32 s43, s1, 0
	s_mov_b32 s69, -2
	v_mov_b32_e32 v1, v0
	v_mov_b32_e32 v2, v0
	v_mov_b32_e32 v3, v0
	v_mov_b32_e32 v4, v0
	v_mov_b32_e32 v5, v0
	v_mov_b32_e32 v6, v0
	v_mov_b32_e32 v7, v0
	v_mov_b32_e32 v16, v0
	v_mov_b32_e32 v17, v0
	v_mov_b32_e32 v18, v0
	v_mov_b32_e32 v19, v0
	v_mov_b32_e32 v20, v0
	v_mov_b32_e32 v21, v0
	v_mov_b32_e32 v22, v0
	v_mov_b32_e32 v23, v0
	v_mov_b32_e32 v32, v0
	v_mov_b32_e32 v33, v0
	v_mov_b32_e32 v34, v0
	v_mov_b32_e32 v35, v0
	v_mov_b32_e32 v36, v0
	v_mov_b32_e32 v37, v0
	v_mov_b32_e32 v38, v0
	v_mov_b32_e32 v39, v0
	v_mov_b32_e32 v48, v0
	v_mov_b32_e32 v49, v0
	v_mov_b32_e32 v50, v0
	v_mov_b32_e32 v51, v0
	v_mov_b32_e32 v52, v0
	v_mov_b32_e32 v53, v0
	v_mov_b32_e32 v54, v0
	v_mov_b32_e32 v55, v0
	v_mov_b32_e32 v8, v0
	v_mov_b32_e32 v9, v0
	v_mov_b32_e32 v10, v0
	v_mov_b32_e32 v11, v0
	v_mov_b32_e32 v12, v0
	v_mov_b32_e32 v13, v0
	v_mov_b32_e32 v14, v0
	v_mov_b32_e32 v15, v0
	v_mov_b32_e32 v24, v0
	v_mov_b32_e32 v25, v0
	v_mov_b32_e32 v26, v0
	v_mov_b32_e32 v27, v0
	v_mov_b32_e32 v28, v0
	v_mov_b32_e32 v29, v0
	v_mov_b32_e32 v30, v0
	v_mov_b32_e32 v31, v0
	v_mov_b32_e32 v40, v0
	v_mov_b32_e32 v41, v0
	v_mov_b32_e32 v42, v0
	v_mov_b32_e32 v43, v0
	v_mov_b32_e32 v44, v0
	v_mov_b32_e32 v45, v0
	v_mov_b32_e32 v46, v0
	v_mov_b32_e32 v47, v0
	v_mov_b32_e32 v56, v0
	v_mov_b32_e32 v57, v0
	v_mov_b32_e32 v58, v0
	v_mov_b32_e32 v59, v0
	v_mov_b32_e32 v60, v0
	v_mov_b32_e32 v61, v0
	v_mov_b32_e32 v62, v0
	v_mov_b32_e32 v63, v0
	v_mov_b32_e32 v64, v0
	v_mov_b32_e32 v65, v0
	v_mov_b32_e32 v66, v0
	v_mov_b32_e32 v67, v0
	v_mov_b32_e32 v68, v0
	v_mov_b32_e32 v69, v0
	v_mov_b32_e32 v70, v0
	v_mov_b32_e32 v71, v0
	v_mov_b32_e32 v76, v0
	v_mov_b32_e32 v77, v0
	v_mov_b32_e32 v78, v0
	v_mov_b32_e32 v79, v0
	v_mov_b32_e32 v84, v0
	v_mov_b32_e32 v85, v0
	v_mov_b32_e32 v86, v0
	v_mov_b32_e32 v87, v0
	v_mov_b32_e32 v96, v0
	v_mov_b32_e32 v97, v0
	v_mov_b32_e32 v98, v0
	v_mov_b32_e32 v99, v0
	v_mov_b32_e32 v100, v0
	v_mov_b32_e32 v101, v0
	v_mov_b32_e32 v102, v0
	v_mov_b32_e32 v103, v0
	v_mov_b32_e32 v104, v0
	v_mov_b32_e32 v105, v0
	v_mov_b32_e32 v106, v0
	v_mov_b32_e32 v107, v0
	v_mov_b32_e32 v112, v0
	v_mov_b32_e32 v113, v0
	v_mov_b32_e32 v114, v0
	v_mov_b32_e32 v115, v0
	v_mov_b32_e32 v72, v0
	v_mov_b32_e32 v73, v0
	v_mov_b32_e32 v74, v0
	v_mov_b32_e32 v75, v0
	v_mov_b32_e32 v80, v0
	v_mov_b32_e32 v81, v0
	v_mov_b32_e32 v82, v0
	v_mov_b32_e32 v83, v0
	v_mov_b32_e32 v88, v0
	v_mov_b32_e32 v89, v0
	v_mov_b32_e32 v90, v0
	v_mov_b32_e32 v91, v0
	v_mov_b32_e32 v92, v0
	v_mov_b32_e32 v93, v0
	v_mov_b32_e32 v94, v0
	v_mov_b32_e32 v95, v0
	v_mov_b32_e32 v108, v0
	v_mov_b32_e32 v109, v0
	v_mov_b32_e32 v110, v0
	v_mov_b32_e32 v111, v0
	v_mov_b32_e32 v116, v0
	v_mov_b32_e32 v117, v0
	v_mov_b32_e32 v118, v0
	v_mov_b32_e32 v119, v0
	v_mov_b32_e32 v120, v0
	v_mov_b32_e32 v121, v0
	v_mov_b32_e32 v122, v0
	v_mov_b32_e32 v123, v0
	v_mov_b32_e32 v124, v0
	v_mov_b32_e32 v125, v0
	v_mov_b32_e32 v126, v0
	v_mov_b32_e32 v127, v0
	s_cmp_lg_u64 s[10:11], 0
	s_cbranch_scc0 .Lgprio_b
	s_setprio 1

; template <class Epi>
; __device__ __forceinline__ void gemm_phase(LAS unsigned char* lds, const Gemm g, const StaticOrder& S, const Epi& E, const int tid) {
;     ...
;         const bool has_next = S.next(ui + 1, nxt);
;         const char* nA = has_next ? PG8_APTR(nxt) : cA; const char* nB = has_next ? PG8_BPTR(nxt) : cB;
;     ...
;         for (int a = 0; a < 2; ++a)
; #pragma unroll
;             for (int b = 0; b < 2; ++b)
; #pragma unroll
;                 for (int m = 0; m < 4; ++m)
; #pragma unroll
;                     for (int n = 0; n < 2; ++n) acc[a][b][m][n] = (f32x4){0.f, 0.f, 0.f, 0.f};
.LBB0_353:
	s_ashr_i32 s49, s48, 31
	s_lshl_b64 s[10:11], s[48:49], 20
	s_add_u32 s52, s38, s10
	s_addc_u32 s53, s39, s11
	s_and_b64 s[10:11], s[40:41], exec
	s_cselect_b32 s10, s53, s1
	s_cselect_b32 s11, s52, s0
	s_ashr_i32 s47, s46, 31
	s_lshl_b64 s[12:13], s[46:47], 20
	v_readlane_b32 s16, v255, 32
	s_add_u32 s12, s16, s12
	v_readlane_b32 s16, v255, 33
	s_addc_u32 s13, s16, s13
	s_and_b64 s[36:37], s[40:41], exec
	s_cselect_b32 s47, s13, s43
	s_cselect_b32 s49, s12, s42
	s_add_u32 s36, s0, 0x80080
	s_addc_u32 s37, s1, 0
	s_add_u32 s69, s42, 0x100
	v_mov_b32_e32 v0, 0
	s_addc_u32 vcc_lo, s43, 0
	s_mov_b32 vcc_hi, -2
	v_mov_b32_e32 v1, v0
	v_mov_b32_e32 v2, v0
	v_mov_b32_e32 v3, v0
	v_mov_b32_e32 v4, v0
	v_mov_b32_e32 v5, v0
	v_mov_b32_e32 v6, v0
	v_mov_b32_e32 v7, v0
	v_mov_b32_e32 v16, v0
	v_mov_b32_e32 v17, v0
	v_mov_b32_e32 v18, v0
	v_mov_b32_e32 v19, v0
	v_mov_b32_e32 v20, v0
	v_mov_b32_e32 v21, v0
	v_mov_b32_e32 v22, v0
	v_mov_b32_e32 v23, v0
	v_mov_b32_e32 v32, v0
	v_mov_b32_e32 v33, v0
	v_mov_b32_e32 v34, v0
	v_mov_b32_e32 v35, v0
	v_mov_b32_e32 v36, v0
	v_mov_b32_e32 v37, v0
	v_mov_b32_e32 v38, v0
	v_mov_b32_e32 v39, v0
	v_mov_b32_e32 v48, v0
	v_mov_b32_e32 v49, v0
	v_mov_b32_e32 v50, v0
	v_mov_b32_e32 v51, v0
	v_mov_b32_e32 v52, v0
	v_mov_b32_e32 v53, v0
	v_mov_b32_e32 v54, v0
	v_mov_b32_e32 v55, v0
	v_mov_b32_e32 v8, v0
	v_mov_b32_e32 v9, v0
	v_mov_b32_e32 v10, v0
	v_mov_b32_e32 v11, v0
	v_mov_b32_e32 v12, v0
	v_mov_b32_e32 v13, v0
	v_mov_b32_e32 v14, v0
	v_mov_b32_e32 v15, v0
	v_mov_b32_e32 v24, v0
	v_mov_b32_e32 v25, v0
	v_mov_b32_e32 v26, v0
	v_mov_b32_e32 v27, v0
	v_mov_b32_e32 v28, v0
	v_mov_b32_e32 v29, v0
	v_mov_b32_e32 v30, v0
	v_mov_b32_e32 v31, v0
	v_mov_b32_e32 v40, v0
	v_mov_b32_e32 v41, v0
	v_mov_b32_e32 v42, v0
	v_mov_b32_e32 v43, v0
	v_mov_b32_e32 v44, v0
	v_mov_b32_e32 v45, v0
	v_mov_b32_e32 v46, v0
	v_mov_b32_e32 v47, v0
	v_mov_b32_e32 v56, v0
	v_mov_b32_e32 v57, v0
	v_mov_b32_e32 v58, v0
	v_mov_b32_e32 v59, v0
	v_mov_b32_e32 v60, v0
	v_mov_b32_e32 v61, v0
	v_mov_b32_e32 v62, v0
	v_mov_b32_e32 v63, v0
	v_mov_b32_e32 v64, v0
	v_mov_b32_e32 v65, v0
	v_mov_b32_e32 v66, v0
	v_mov_b32_e32 v67, v0
	v_mov_b32_e32 v68, v0
	v_mov_b32_e32 v69, v0
	v_mov_b32_e32 v70, v0
	v_mov_b32_e32 v71, v0
	v_mov_b32_e32 v80, v0
	v_mov_b32_e32 v81, v0
	v_mov_b32_e32 v82, v0
	v_mov_b32_e32 v83, v0
	v_mov_b32_e32 v84, v0
	v_mov_b32_e32 v85, v0
	v_mov_b32_e32 v86, v0
	v_mov_b32_e32 v87, v0
	v_mov_b32_e32 v96, v0
	v_mov_b32_e32 v97, v0
	v_mov_b32_e32 v98, v0
	v_mov_b32_e32 v99, v0
	v_mov_b32_e32 v100, v0
	v_mov_b32_e32 v101, v0
	v_mov_b32_e32 v102, v0
	v_mov_b32_e32 v103, v0
	v_mov_b32_e32 v112, v0
	v_mov_b32_e32 v113, v0
	v_mov_b32_e32 v114, v0
	v_mov_b32_e32 v115, v0
	v_mov_b32_e32 v116, v0
	v_mov_b32_e32 v117, v0
	v_mov_b32_e32 v118, v0
	v_mov_b32_e32 v119, v0
	v_mov_b32_e32 v72, v0
	v_mov_b32_e32 v73, v0
	v_mov_b32_e32 v74, v0
	v_mov_b32_e32 v75, v0
	v_mov_b32_e32 v76, v0
	v_mov_b32_e32 v77, v0
	v_mov_b32_e32 v78, v0
	v_mov_b32_e32 v79, v0
	v_mov_b32_e32 v88, v0
	v_mov_b32_e32 v89, v0
	v_mov_b32_e32 v90, v0
	v_mov_b32_e32 v91, v0
	v_mov_b32_e32 v92, v0
	v_mov_b32_e32 v93, v0
	v_mov_b32_e32 v94, v0
	v_mov_b32_e32 v95, v0
	v_mov_b32_e32 v104, v0
	v_mov_b32_e32 v105, v0
	v_mov_b32_e32 v106, v0
	v_mov_b32_e32 v107, v0
	v_mov_b32_e32 v108, v0
	v_mov_b32_e32 v109, v0
	v_mov_b32_e32 v110, v0
	v_mov_b32_e32 v111, v0
	v_mov_b32_e32 v120, v0
	v_mov_b32_e32 v121, v0
	v_mov_b32_e32 v122, v0
	v_mov_b32_e32 v123, v0
	v_mov_b32_e32 v124, v0
	v_mov_b32_e32 v125, v0
	v_mov_b32_e32 v126, v0
	v_mov_b32_e32 v127, v0
	s_cmp_lg_u64 s[34:35], 0
	s_cbranch_scc0 .Lgprio_c
	s_setprio 1

; template <class Epi>
; __device__ __forceinline__ void gemm_phase(LAS unsigned char* lds, const Gemm g, const StaticOrder& S, const Epi& E, const int tid) {
;     ...
;         const bool has_next = S.next(ui + 1, nxt);
;         const char* nA = has_next ? PG8_APTR(nxt) : cA; const char* nB = has_next ? PG8_BPTR(nxt) : cB;
.LBB0_822:
	s_lshl_b64 s[0:1], s[44:45], 22
	v_readlane_b32 s14, v255, 24
	s_add_u32 s24, s14, s0
	v_readlane_b32 s0, v255, 25
	s_addc_u32 s25, s0, s1
	s_ashr_i32 s35, s34, 31
	s_lshl_b64 s[0:1], s[34:35], 19
	s_add_u32 s0, s24, s0
	s_addc_u32 s1, s25, s1
	s_and_b64 s[24:25], s[42:43], exec
	s_cselect_b32 s35, s1, s49
	s_cselect_b32 s45, s0, s48
	s_add_u32 s68, s48, 0x100
	s_addc_u32 s69, s49, 0
	s_mov_b32 s96, -2
	s_cmp_lg_u64 s[12:13], 0
	s_cbranch_scc0 .Lgprio_d
	s_setprio 1

; template <class Epi>
; __device__ __forceinline__ void gemm_phase(LAS unsigned char* lds, const Gemm g, const StaticOrder& S, const Epi& E, const int tid) {
;     ...
;         const bool has_next = S.next(ui + 1, nxt);
;         const char* nA = has_next ? PG8_APTR(nxt) : cA; const char* nB = has_next ? PG8_BPTR(nxt) : cB;
;         for (int t = 0; t < nt; t += 2) {
;             const bool last = (t == nt - 2);
;             const char* a1 = cA + (size_t)(t + 1) * kstep;
;             const char* a2 = last ? nA : cA + (size_t)(t + 2) * kstep; const char* b2 = last ? nB : cB + (size_t)(t + 2) * kstep;
;             const char* a3 = a2 + kstep; const char* b3 = b2 + kstep;
;     ...
;         if (!(Epi::CHAIN && cur.n + 1 < S.NS)) {
; #pragma unroll
;         for (int a = 0; a < 2; ++a)
; #pragma unroll
;             for (int b = 0; b < 2; ++b)
; #pragma unroll
;                 for (int m = 0; m < 4; ++m)
; #pragma unroll
;                     for (int n = 0; n < 2; ++n) acc[a][b][m][n] = (f32x4){0.f, 0.f, 0.f, 0.f};
;         }
;         cur = nxt; cA = nA; cB = nB; ++ui;
.LBB0_892:
	s_ashr_i32 s11, s10, 31
	s_lshl_b64 s[12:13], s[10:11], 20
	s_add_u32 s12, s58, s12
	s_addc_u32 s13, s59, s13
	s_and_b64 s[14:15], s[40:41], exec
	s_cselect_b32 s11, s13, s17
	s_cselect_b32 s49, s12, s16
	s_ashr_i32 s9, s8, 31
	s_lshl_b64 s[14:15], s[8:9], 20
	s_add_u32 s14, s27, s14
	s_addc_u32 s15, s34, s15
	s_and_b64 s[18:19], s[40:41], exec
	s_cselect_b32 s9, s15, s1
	s_cselect_b32 s52, s14, s0
	s_add_u32 s16, s16, 0x80080
	s_addc_u32 s17, s17, 0
	s_add_u32 s53, s0, 0x100
	v_mov_b32_e32 v0, 0
	s_addc_u32 s56, s1, 0
	s_mov_b32 s57, -2
	v_mov_b32_e32 v1, v0
	v_mov_b32_e32 v2, v0
	v_mov_b32_e32 v3, v0
	v_mov_b32_e32 v4, v0
	v_mov_b32_e32 v5, v0
	v_mov_b32_e32 v6, v0
	v_mov_b32_e32 v7, v0
	v_mov_b32_e32 v16, v0
	v_mov_b32_e32 v17, v0
	v_mov_b32_e32 v18, v0
	v_mov_b32_e32 v19, v0
	v_mov_b32_e32 v20, v0
	v_mov_b32_e32 v21, v0
	v_mov_b32_e32 v22, v0
	v_mov_b32_e32 v23, v0
	v_mov_b32_e32 v32, v0
	v_mov_b32_e32 v33, v0
	v_mov_b32_e32 v34, v0
	v_mov_b32_e32 v35, v0
	v_mov_b32_e32 v36, v0
	v_mov_b32_e32 v37, v0
	v_mov_b32_e32 v38, v0
	v_mov_b32_e32 v39, v0
	v_mov_b32_e32 v48, v0
	v_mov_b32_e32 v49, v0
	v_mov_b32_e32 v50, v0
	v_mov_b32_e32 v51, v0
	v_mov_b32_e32 v52, v0
	v_mov_b32_e32 v53, v0
	v_mov_b32_e32 v54, v0
	v_mov_b32_e32 v55, v0
	v_mov_b32_e32 v8, v0
	v_mov_b32_e32 v9, v0
	v_mov_b32_e32 v10, v0
	v_mov_b32_e32 v11, v0
	v_mov_b32_e32 v12, v0
	v_mov_b32_e32 v13, v0
	v_mov_b32_e32 v14, v0
	v_mov_b32_e32 v15, v0
	v_mov_b32_e32 v24, v0
	v_mov_b32_e32 v25, v0
	v_mov_b32_e32 v26, v0
	v_mov_b32_e32 v27, v0
	v_mov_b32_e32 v28, v0
	v_mov_b32_e32 v29, v0
	v_mov_b32_e32 v30, v0
	v_mov_b32_e32 v31, v0
	v_mov_b32_e32 v40, v0
	v_mov_b32_e32 v41, v0
	v_mov_b32_e32 v42, v0
	v_mov_b32_e32 v43, v0
	v_mov_b32_e32 v44, v0
	v_mov_b32_e32 v45, v0
	v_mov_b32_e32 v46, v0
	v_mov_b32_e32 v47, v0
	v_mov_b32_e32 v56, v0
	v_mov_b32_e32 v57, v0
	v_mov_b32_e32 v58, v0
	v_mov_b32_e32 v59, v0
	v_mov_b32_e32 v60, v0
	v_mov_b32_e32 v61, v0
	v_mov_b32_e32 v62, v0
	v_mov_b32_e32 v63, v0
	v_mov_b32_e32 v80, v0
	v_mov_b32_e32 v81, v0
	v_mov_b32_e32 v82, v0
	v_mov_b32_e32 v83, v0
	v_mov_b32_e32 v84, v0
	v_mov_b32_e32 v85, v0
	v_mov_b32_e32 v86, v0
	v_mov_b32_e32 v87, v0
	v_mov_b32_e32 v92, v0
	v_mov_b32_e32 v93, v0
	v_mov_b32_e32 v94, v0
	v_mov_b32_e32 v95, v0
	v_mov_b32_e32 v100, v0
	v_mov_b32_e32 v101, v0
	v_mov_b32_e32 v102, v0
	v_mov_b32_e32 v103, v0
	v_mov_b32_e32 v112, v0
	v_mov_b32_e32 v113, v0
	v_mov_b32_e32 v114, v0
	v_mov_b32_e32 v115, v0
	v_mov_b32_e32 v116, v0
	v_mov_b32_e32 v117, v0
	v_mov_b32_e32 v118, v0
	v_mov_b32_e32 v119, v0
	v_mov_b32_e32 v128, v0
	v_mov_b32_e32 v129, v0
	v_mov_b32_e32 v130, v0
	v_mov_b32_e32 v131, v0
	v_mov_b32_e32 v132, v0
	v_mov_b32_e32 v133, v0
	v_mov_b32_e32 v134, v0
	v_mov_b32_e32 v135, v0
	v_mov_b32_e32 v88, v0
	v_mov_b32_e32 v89, v0
	v_mov_b32_e32 v90, v0
	v_mov_b32_e32 v91, v0
	v_mov_b32_e32 v96, v0
	v_mov_b32_e32 v97, v0
	v_mov_b32_e32 v98, v0
	v_mov_b32_e32 v99, v0
	v_mov_b32_e32 v104, v0
	v_mov_b32_e32 v105, v0
	v_mov_b32_e32 v106, v0
	v_mov_b32_e32 v107, v0
	v_mov_b32_e32 v108, v0
	v_mov_b32_e32 v109, v0
	v_mov_b32_e32 v110, v0
	v_mov_b32_e32 v111, v0
	v_mov_b32_e32 v120, v0
	v_mov_b32_e32 v121, v0
	v_mov_b32_e32 v122, v0
	v_mov_b32_e32 v123, v0
	v_mov_b32_e32 v124, v0
	v_mov_b32_e32 v125, v0
	v_mov_b32_e32 v126, v0
	v_mov_b32_e32 v127, v0
	v_mov_b32_e32 v136, v0
	v_mov_b32_e32 v137, v0
	v_mov_b32_e32 v138, v0
	v_mov_b32_e32 v139, v0
	v_mov_b32_e32 v140, v0
	v_mov_b32_e32 v141, v0
	v_mov_b32_e32 v142, v0
	v_mov_b32_e32 v143, v0
	s_cmp_lg_u64 s[6:7], 0
	s_cbranch_scc0 .Lgprio_e
	s_setprio 1

; template <class Epi>
; __device__ __forceinline__ void gemm_phase(LAS unsigned char* lds, const Gemm g, const StaticOrder& S, const Epi& E, const int tid) {
;     ...
;         const bool has_next = S.next(ui + 1, nxt);
;         const char* nA = has_next ? PG8_APTR(nxt) : cA; const char* nB = has_next ? PG8_BPTR(nxt) : cB;
;         for (int t = 0; t < nt; t += 2) {
;             const bool last = (t == nt - 2);
;             const char* a1 = cA + (size_t)(t + 1) * kstep;
;             const char* a2 = last ? nA : cA + (size_t)(t + 2) * kstep; const char* b2 = last ? nB : cB + (size_t)(t + 2) * kstep;
;             const char* a3 = a2 + kstep; const char* b3 = b2 + kstep;
;     ...
;         if (!(Epi::CHAIN && cur.n + 1 < S.NS)) {
; #pragma unroll
;         for (int a = 0; a < 2; ++a)
; #pragma unroll
;             for (int b = 0; b < 2; ++b)
; #pragma unroll
;                 for (int m = 0; m < 4; ++m)
; #pragma unroll
;                     for (int n = 0; n < 2; ++n) acc[a][b][m][n] = (f32x4){0.f, 0.f, 0.f, 0.f};
;         }
;         cur = nxt; cA = nA; cB = nB; ++ui;
.LBB0_1003:
	s_ashr_i32 s13, s12, 31
	s_lshl_b64 s[14:15], s[12:13], 20
	s_add_u32 s14, s58, s14
	s_addc_u32 s15, s59, s15
	s_and_b64 s[16:17], s[38:39], exec
	s_cselect_b32 s13, s15, s19
	s_cselect_b32 s49, s14, s18
	s_ashr_i32 s11, s10, 31
	s_lshl_b64 s[16:17], s[10:11], 20
	s_add_u32 s16, s36, s16
	s_addc_u32 s17, s37, s17
	s_and_b64 s[24:25], s[38:39], exec
	s_cselect_b32 s11, s17, s1
	s_cselect_b32 s52, s16, s0
	s_add_u32 s18, s18, 0x80080
	s_addc_u32 s19, s19, 0
	s_add_u32 s53, s0, 0x100
	v_mov_b32_e32 v0, 0
	s_addc_u32 s56, s1, 0
	s_mov_b32 s57, -2
	v_mov_b32_e32 v1, v0
	v_mov_b32_e32 v2, v0
	v_mov_b32_e32 v3, v0
	v_mov_b32_e32 v8, v0
	v_mov_b32_e32 v9, v0
	v_mov_b32_e32 v10, v0
	v_mov_b32_e32 v11, v0
	v_mov_b32_e32 v16, v0
	v_mov_b32_e32 v17, v0
	v_mov_b32_e32 v18, v0
	v_mov_b32_e32 v19, v0
	v_mov_b32_e32 v24, v0
	v_mov_b32_e32 v25, v0
	v_mov_b32_e32 v26, v0
	v_mov_b32_e32 v27, v0
	v_mov_b32_e32 v32, v0
	v_mov_b32_e32 v33, v0
	v_mov_b32_e32 v34, v0
	v_mov_b32_e32 v35, v0
	v_mov_b32_e32 v40, v0
	v_mov_b32_e32 v41, v0
	v_mov_b32_e32 v42, v0
	v_mov_b32_e32 v43, v0
	v_mov_b32_e32 v48, v0
	v_mov_b32_e32 v49, v0
	v_mov_b32_e32 v50, v0
	v_mov_b32_e32 v51, v0
	v_mov_b32_e32 v56, v0
	v_mov_b32_e32 v57, v0
	v_mov_b32_e32 v58, v0
	v_mov_b32_e32 v59, v0
	v_mov_b32_e32 v4, v0
	v_mov_b32_e32 v5, v0
	v_mov_b32_e32 v6, v0
	v_mov_b32_e32 v7, v0
	v_mov_b32_e32 v12, v0
	v_mov_b32_e32 v13, v0
	v_mov_b32_e32 v14, v0
	v_mov_b32_e32 v15, v0
	v_mov_b32_e32 v20, v0
	v_mov_b32_e32 v21, v0
	v_mov_b32_e32 v22, v0
	v_mov_b32_e32 v23, v0
	v_mov_b32_e32 v28, v0
	v_mov_b32_e32 v29, v0
	v_mov_b32_e32 v30, v0
	v_mov_b32_e32 v31, v0
	v_mov_b32_e32 v36, v0
	v_mov_b32_e32 v37, v0
	v_mov_b32_e32 v38, v0
	v_mov_b32_e32 v39, v0
	v_mov_b32_e32 v44, v0
	v_mov_b32_e32 v45, v0
	v_mov_b32_e32 v46, v0
	v_mov_b32_e32 v47, v0
	v_mov_b32_e32 v52, v0
	v_mov_b32_e32 v53, v0
	v_mov_b32_e32 v54, v0
	v_mov_b32_e32 v55, v0
	v_mov_b32_e32 v60, v0
	v_mov_b32_e32 v61, v0
	v_mov_b32_e32 v62, v0
	v_mov_b32_e32 v63, v0
	v_mov_b32_e32 v64, v0
	v_mov_b32_e32 v65, v0
	v_mov_b32_e32 v66, v0
	v_mov_b32_e32 v67, v0
	v_mov_b32_e32 v72, v0
	v_mov_b32_e32 v73, v0
	v_mov_b32_e32 v74, v0
	v_mov_b32_e32 v75, v0
	v_mov_b32_e32 v80, v0
	v_mov_b32_e32 v81, v0
	v_mov_b32_e32 v82, v0
	v_mov_b32_e32 v83, v0
	v_mov_b32_e32 v88, v0
	v_mov_b32_e32 v89, v0
	v_mov_b32_e32 v90, v0
	v_mov_b32_e32 v91, v0
	v_mov_b32_e32 v96, v0
	v_mov_b32_e32 v97, v0
	v_mov_b32_e32 v98, v0
	v_mov_b32_e32 v99, v0
	v_mov_b32_e32 v104, v0
	v_mov_b32_e32 v105, v0
	v_mov_b32_e32 v106, v0
	v_mov_b32_e32 v107, v0
	v_mov_b32_e32 v112, v0
	v_mov_b32_e32 v113, v0
	v_mov_b32_e32 v114, v0
	v_mov_b32_e32 v115, v0
	v_mov_b32_e32 v120, v0
	v_mov_b32_e32 v121, v0
	v_mov_b32_e32 v122, v0
	v_mov_b32_e32 v123, v0
	v_mov_b32_e32 v68, v0
	v_mov_b32_e32 v69, v0
	v_mov_b32_e32 v70, v0
	v_mov_b32_e32 v71, v0
	v_mov_b32_e32 v76, v0
	v_mov_b32_e32 v77, v0
	v_mov_b32_e32 v78, v0
	v_mov_b32_e32 v79, v0
	v_mov_b32_e32 v84, v0
	v_mov_b32_e32 v85, v0
	v_mov_b32_e32 v86, v0
	v_mov_b32_e32 v87, v0
	v_mov_b32_e32 v92, v0
	v_mov_b32_e32 v93, v0
	v_mov_b32_e32 v94, v0
	v_mov_b32_e32 v95, v0
	v_mov_b32_e32 v100, v0
	v_mov_b32_e32 v101, v0
	v_mov_b32_e32 v102, v0
	v_mov_b32_e32 v103, v0
	v_mov_b32_e32 v108, v0
	v_mov_b32_e32 v109, v0
	v_mov_b32_e32 v110, v0
	v_mov_b32_e32 v111, v0
	v_mov_b32_e32 v116, v0
	v_mov_b32_e32 v117, v0
	v_mov_b32_e32 v118, v0
	v_mov_b32_e32 v119, v0
	v_mov_b32_e32 v124, v0
	v_mov_b32_e32 v125, v0
	v_mov_b32_e32 v126, v0
	v_mov_b32_e32 v127, v0
	s_cmp_lg_u64 s[8:9], 0
	s_cbranch_scc0 .Lgprio_f
	s_setprio 1

; template <class Epi>
; __device__ __forceinline__ void gemm_phase(LAS unsigned char* lds, const Gemm g, const StaticOrder& S, const Epi& E, const int tid) {
;     ...
;         const bool has_next = S.next(ui + 1, nxt);
;         const char* nA = has_next ? PG8_APTR(nxt) : cA; const char* nB = has_next ? PG8_BPTR(nxt) : cB;
;         for (int t = 0; t < nt; t += 2) {
;     ...
;         if (!(Epi::CHAIN && cur.n + 1 < S.NS)) {
; #pragma unroll
;         for (int a = 0; a < 2; ++a)
; #pragma unroll
;             for (int b = 0; b < 2; ++b)
; #pragma unroll
;                 for (int m = 0; m < 4; ++m)
; #pragma unroll
;                     for (int n = 0; n < 2; ++n) acc[a][b][m][n] = (f32x4){0.f, 0.f, 0.f, 0.f};
;         }
;         cur = nxt; cA = nA; cB = nB; ++ui;
.LBB0_1075:
	s_add_u32 s38, s0, 0x100
	v_mov_b32_e32 v0, 0
	s_addc_u32 s39, s1, 0
	s_mov_b32 s53, -2
	v_mov_b32_e32 v1, v0
	v_mov_b32_e32 v2, v0
	v_mov_b32_e32 v3, v0
	v_mov_b32_e32 v4, v0
	v_mov_b32_e32 v5, v0
	v_mov_b32_e32 v6, v0
	v_mov_b32_e32 v7, v0
	v_mov_b32_e32 v16, v0
	v_mov_b32_e32 v17, v0
	v_mov_b32_e32 v18, v0
	v_mov_b32_e32 v19, v0
	v_mov_b32_e32 v20, v0
	v_mov_b32_e32 v21, v0
	v_mov_b32_e32 v22, v0
	v_mov_b32_e32 v23, v0
	v_mov_b32_e32 v32, v0
	v_mov_b32_e32 v33, v0
	v_mov_b32_e32 v34, v0
	v_mov_b32_e32 v35, v0
	v_mov_b32_e32 v36, v0
	v_mov_b32_e32 v37, v0
	v_mov_b32_e32 v38, v0
	v_mov_b32_e32 v39, v0
	v_mov_b32_e32 v48, v0
	v_mov_b32_e32 v49, v0
	v_mov_b32_e32 v50, v0
	v_mov_b32_e32 v51, v0
	v_mov_b32_e32 v52, v0
	v_mov_b32_e32 v53, v0
	v_mov_b32_e32 v54, v0
	v_mov_b32_e32 v55, v0
	v_mov_b32_e32 v8, v0
	v_mov_b32_e32 v9, v0
	v_mov_b32_e32 v10, v0
	v_mov_b32_e32 v11, v0
	v_mov_b32_e32 v12, v0
	v_mov_b32_e32 v13, v0
	v_mov_b32_e32 v14, v0
	v_mov_b32_e32 v15, v0
	v_mov_b32_e32 v24, v0
	v_mov_b32_e32 v25, v0
	v_mov_b32_e32 v26, v0
	v_mov_b32_e32 v27, v0
	v_mov_b32_e32 v28, v0
	v_mov_b32_e32 v29, v0
	v_mov_b32_e32 v30, v0
	v_mov_b32_e32 v31, v0
	v_mov_b32_e32 v40, v0
	v_mov_b32_e32 v41, v0
	v_mov_b32_e32 v42, v0
	v_mov_b32_e32 v43, v0
	v_mov_b32_e32 v44, v0
	v_mov_b32_e32 v45, v0
	v_mov_b32_e32 v46, v0
	v_mov_b32_e32 v47, v0
	v_mov_b32_e32 v56, v0
	v_mov_b32_e32 v57, v0
	v_mov_b32_e32 v58, v0
	v_mov_b32_e32 v59, v0
	v_mov_b32_e32 v60, v0
	v_mov_b32_e32 v61, v0
	v_mov_b32_e32 v62, v0
	v_mov_b32_e32 v63, v0
	v_mov_b32_e32 v64, v0
	v_mov_b32_e32 v65, v0
	v_mov_b32_e32 v66, v0
	v_mov_b32_e32 v67, v0
	v_mov_b32_e32 v68, v0
	v_mov_b32_e32 v69, v0
	v_mov_b32_e32 v70, v0
	v_mov_b32_e32 v71, v0
	v_mov_b32_e32 v76, v0
	v_mov_b32_e32 v77, v0
	v_mov_b32_e32 v78, v0
	v_mov_b32_e32 v79, v0
	v_mov_b32_e32 v84, v0
	v_mov_b32_e32 v85, v0
	v_mov_b32_e32 v86, v0
	v_mov_b32_e32 v87, v0
	v_mov_b32_e32 v96, v0
	v_mov_b32_e32 v97, v0
	v_mov_b32_e32 v98, v0
	v_mov_b32_e32 v99, v0
	v_mov_b32_e32 v100, v0
	v_mov_b32_e32 v101, v0
	v_mov_b32_e32 v102, v0
	v_mov_b32_e32 v103, v0
	v_mov_b32_e32 v112, v0
	v_mov_b32_e32 v113, v0
	v_mov_b32_e32 v114, v0
	v_mov_b32_e32 v115, v0
	v_mov_b32_e32 v116, v0
	v_mov_b32_e32 v117, v0
	v_mov_b32_e32 v118, v0
	v_mov_b32_e32 v119, v0
	v_mov_b32_e32 v72, v0
	v_mov_b32_e32 v73, v0
	v_mov_b32_e32 v74, v0
	v_mov_b32_e32 v75, v0
	v_mov_b32_e32 v80, v0
	v_mov_b32_e32 v81, v0
	v_mov_b32_e32 v82, v0
	v_mov_b32_e32 v83, v0
	v_mov_b32_e32 v88, v0
	v_mov_b32_e32 v89, v0
	v_mov_b32_e32 v90, v0
	v_mov_b32_e32 v91, v0
	v_mov_b32_e32 v92, v0
	v_mov_b32_e32 v93, v0
	v_mov_b32_e32 v94, v0
	v_mov_b32_e32 v95, v0
	v_mov_b32_e32 v104, v0
	v_mov_b32_e32 v105, v0
	v_mov_b32_e32 v106, v0
	v_mov_b32_e32 v107, v0
	v_mov_b32_e32 v108, v0
	v_mov_b32_e32 v109, v0
	v_mov_b32_e32 v110, v0
	v_mov_b32_e32 v111, v0
	v_mov_b32_e32 v120, v0
	v_mov_b32_e32 v121, v0
	v_mov_b32_e32 v122, v0
	v_mov_b32_e32 v123, v0
	v_mov_b32_e32 v124, v0
	v_mov_b32_e32 v125, v0
	v_mov_b32_e32 v126, v0
	v_mov_b32_e32 v127, v0
	s_cmp_lg_u64 s[6:7], 0
	s_cbranch_scc0 .Lgprio_g
	s_setprio 1
